# P0 max|g_k_nope| by batched 16-byte loads instead of 32 serialized loads; sample-attention q' staging: the 8 gains of a chunk in two 16-byte loads issued with the q chunk
# speedup vs baseline: 1.0246x; 1.0028x over previous
.LBB0_176:
	v_readlane_b32 s3, v253, 21
	s_waitcnt vmcnt(2)
	s_nop 0
	v_or_b32_e32 v2, s3, v1
	v_cmp_eq_u32_e32 vcc, 0, v2
	s_and_saveexec_b64 s[4:5], vcc
	s_cbranch_execz .LBB0_183
	s_load_dwordx16 s[16:31], s[0:1], 0x80
	v_mov_b32_e32 v36, 0
	s_waitcnt lgkmcnt(0)
	global_load_dwordx4 v[4:7], v36, s[16:17]
	global_load_dwordx4 v[8:11], v36, s[16:17] offset:16
	global_load_dwordx4 v[12:15], v36, s[16:17] offset:32
	global_load_dwordx4 v[16:19], v36, s[16:17] offset:48
	global_load_dwordx4 v[20:23], v36, s[16:17] offset:64
	global_load_dwordx4 v[24:27], v36, s[16:17] offset:80
	global_load_dwordx4 v[28:31], v36, s[16:17] offset:96
	global_load_dwordx4 v[32:35], v36, s[16:17] offset:112
	s_waitcnt vmcnt(0)
	v_max3_f32 v2, |v4|, 0, |v5|
	v_max3_f32 v2, v2, |v6|, |v7|
	v_max3_f32 v2, v2, |v8|, |v9|
	v_max3_f32 v2, v2, |v10|, |v11|
	v_max3_f32 v2, v2, |v12|, |v13|
	v_max3_f32 v2, v2, |v14|, |v15|
	v_max3_f32 v2, v2, |v16|, |v17|
	v_max3_f32 v2, v2, |v18|, |v19|
	v_max3_f32 v2, v2, |v20|, |v21|
	v_max3_f32 v2, v2, |v22|, |v23|
	v_max3_f32 v2, v2, |v24|, |v25|
	v_max3_f32 v2, v2, |v26|, |v27|
	v_max3_f32 v2, v2, |v28|, |v29|
	v_max3_f32 v2, v2, |v30|, |v31|
	v_max3_f32 v2, v2, |v32|, |v33|
	v_max3_f32 v2, v2, |v34|, |v35|
	global_load_dwordx4 v[4:7], v36, s[16:17] offset:128
	global_load_dwordx4 v[8:11], v36, s[16:17] offset:144
	global_load_dwordx4 v[12:15], v36, s[16:17] offset:160
	global_load_dwordx4 v[16:19], v36, s[16:17] offset:176
	global_load_dwordx4 v[20:23], v36, s[16:17] offset:192
	global_load_dwordx4 v[24:27], v36, s[16:17] offset:208
	global_load_dwordx4 v[28:31], v36, s[16:17] offset:224
	global_load_dwordx4 v[32:35], v36, s[16:17] offset:240
	s_waitcnt vmcnt(0)
	v_max3_f32 v2, v2, |v4|, |v5|
	v_max3_f32 v2, v2, |v6|, |v7|
	v_max3_f32 v2, v2, |v8|, |v9|
	v_max3_f32 v2, v2, |v10|, |v11|
	v_max3_f32 v2, v2, |v12|, |v13|
	v_max3_f32 v2, v2, |v14|, |v15|
	v_max3_f32 v2, v2, |v16|, |v17|
	v_max3_f32 v2, v2, |v18|, |v19|
	v_max3_f32 v2, v2, |v20|, |v21|
	v_max3_f32 v2, v2, |v22|, |v23|
	v_max3_f32 v2, v2, |v24|, |v25|
	v_max3_f32 v2, v2, |v26|, |v27|
	v_max3_f32 v2, v2, |v28|, |v29|
	v_max3_f32 v2, v2, |v30|, |v31|
	v_max3_f32 v2, v2, |v32|, |v33|
	v_max3_f32 v2, v2, |v34|, |v35|

.LBB0_783:
	s_mov_b32 s10, 0x2aaaaaab
	v_mul_hi_i32 v2, v10, s10
	v_lshrrev_b32_e32 v3, 31, v2
	v_ashrrev_i32_e32 v2, 1, v2
	s_movk_i32 s10, 0x300
	v_add_u32_e32 v14, v2, v3
	v_cmp_gt_i32_e32 vcc, s10, v10
	v_mov_b32_e32 v5, 0
	v_mov_b32_e32 v4, 0
	v_mov_b32_e32 v3, 0
	v_mov_b32_e32 v2, 0
	s_and_saveexec_b64 s[12:13], vcc
	s_cbranch_execz .LBB0_782
	v_ashrrev_i32_e32 v2, 3, v14
	v_readlane_b32 s40, v254, 28
	v_and_or_b32 v4, v14, 7, s4
	v_mov_b32_e32 v5, s5
	v_ashrrev_i32_e32 v3, 31, v2
	v_readlane_b32 s54, v254, 42
	v_readlane_b32 s55, v254, 43
	s_movk_i32 s10, 0xffa0
	v_lshl_add_u64 v[2:3], v[4:5], 3, v[2:3]
	v_mov_b64_e32 v[4:5], s[54:55]
	v_mad_u64_u32 v[12:13], s[10:11], v14, s10, v[8:9]
	v_mad_u64_u32 v[4:5], s[10:11], v2, s27, v[4:5]
	v_mad_i32_i24 v5, v3, s27, v5
	v_ashrrev_i32_e32 v13, 31, v12
	v_lshl_add_u64 v[2:3], v[12:13], 1, v[4:5]
	global_load_dwordx4 v[2:5], v[2:3], off
	v_readlane_b32 s41, v254, 29
	v_readlane_b32 s42, v254, 30
	v_readlane_b32 s43, v254, 31
	v_readlane_b32 s44, v254, 32
	v_readlane_b32 s45, v254, 33
	v_readlane_b32 s46, v254, 34
	v_readlane_b32 s47, v254, 35
	v_readlane_b32 s48, v254, 36
	v_readlane_b32 s49, v254, 37
	v_readlane_b32 s50, v254, 38
	v_readlane_b32 s51, v254, 39
	v_readlane_b32 s52, v254, 40
	v_readlane_b32 s53, v254, 41
	v_readlane_b32 s40, v253, 40
	v_mad_u64_u32 v[16:17], s[10:11], v14, -12, v[10:11]
	v_readlane_b32 s41, v253, 41
	v_cmp_gt_i32_e32 vcc, 8, v16
	v_readlane_b32 s42, v253, 42
	v_lshl_add_u64 v[12:13], v[12:13], 2, s[40:41]
	v_readlane_b32 s43, v253, 43
	v_readlane_b32 s44, v253, 44
	v_readlane_b32 s45, v253, 45
	v_readlane_b32 s46, v253, 46
	v_readlane_b32 s47, v253, 47
	v_readlane_b32 s48, v253, 48
	v_readlane_b32 s49, v253, 49
	v_readlane_b32 s50, v253, 50
	v_readlane_b32 s51, v253, 51
	v_readlane_b32 s52, v253, 52
	v_readlane_b32 s53, v253, 53
	v_readlane_b32 s54, v253, 54
	v_readlane_b32 s55, v253, 55
	v_mov_b32_e32 v20, 1.0
	v_mov_b32_e32 v21, 1.0
	v_mov_b32_e32 v22, 1.0
	v_mov_b32_e32 v23, 1.0
	v_mov_b32_e32 v24, 1.0
	v_mov_b32_e32 v25, 1.0
	v_mov_b32_e32 v26, 1.0
	v_mov_b32_e32 v27, 1.0
	s_and_saveexec_b64 s[10:11], vcc
	s_cbranch_execz .Lsa_qs_nog
	global_load_dwordx4 v[20:23], v[12:13], off
	global_load_dwordx4 v[24:27], v[12:13], off offset:16
.Lsa_qs_nog:
	s_or_b64 exec, exec, s[10:11]
	s_waitcnt vmcnt(0)
	v_lshlrev_b32_e32 v15, 16, v2
	v_and_b32_e32 v2, 0xffff0000, v2
	v_lshlrev_b32_e32 v16, 16, v3
	v_and_b32_e32 v3, 0xffff0000, v3
	v_lshlrev_b32_e32 v17, 16, v4
	v_and_b32_e32 v4, 0xffff0000, v4
	v_lshlrev_b32_e32 v18, 16, v5
	v_and_b32_e32 v5, 0xffff0000, v5
	v_mul_f32_e32 v15, 0x3fb8aa3b, v15
	v_mul_f32_e32 v2, 0x3fb8aa3b, v2
	v_mul_f32_e32 v16, 0x3fb8aa3b, v16
	v_mul_f32_e32 v3, 0x3fb8aa3b, v3
	v_mul_f32_e32 v17, 0x3fb8aa3b, v17
	v_mul_f32_e32 v4, 0x3fb8aa3b, v4
	v_mul_f32_e32 v18, 0x3fb8aa3b, v18
	v_mul_f32_e32 v5, 0x3fb8aa3b, v5
	v_mul_f32_e32 v15, v15, v20
	v_mul_f32_e32 v2, v2, v21
	v_mul_f32_e32 v16, v16, v22
	v_mul_f32_e32 v3, v3, v23
	v_mul_f32_e32 v17, v17, v24
	v_mul_f32_e32 v4, v4, v25
	v_mul_f32_e32 v18, v18, v26
	v_mul_f32_e32 v5, v5, v27
	s_branch .LBB0_781
